# attention item order: every wave does its two memory cross-attention items first, then the NSA quarters in ascending time
# speedup vs baseline: 1.0077x; 1.0077x over previous
; __device__ __forceinline__ void attention_phase(const Ctx& C) {
;     const int bxx = C.gw / NWAVES; const bool xmode = (C.G & 7) == 0;
;     const int x = bxx & 7, rank = xmode ? (bxx >> 3) * NWAVES + C.wave : C.gw, nrank = xmode ? (C.G >> 3) * NWAVES : C.NGW, nitem = xmode ? 1536 : 12288;
;     const int nper = (nitem + nrank - 1) / nrank, nmem_it = xmode ? (512 + nrank - 1) / nrank : 0; const bool flip = xmode && (nitem % nrank == 0); const int rot = flip ? ((C.wave * 3) >> 3) * 2 : 0;
;     for (int k0 = 0; k0 < nper; ++k0) {
;         const int kk = flip ? (k0 + rot) % nper : k0; const int i = rank + kk * nrank; if (i >= nitem) continue;
.LBB0_646:
	v_readlane_b32 s2, v254, 30
	v_readlane_b32 s3, v254, 31
	s_andn2_b64 vcc, exec, s[2:3]
	s_cbranch_vccnz .LBB0_886
	s_ashr_i32 s2, s1, 6
	s_lshl_b32 s0, s0, 3
	s_add_i32 s3, s0, s2
	s_ashr_i32 s0, s3, 31
	s_lshr_b32 s0, s0, 29
	s_add_i32 s0, s3, s0
	s_mul_i32 s1, s2, 3
	s_ashr_i32 s4, s0, 3
	s_ashr_i32 s1, s1, 2
	s_and_b32 s0, s4, -8
	s_mov_b32 s8, 4
	s_add_i32 s5, s0, s2
	v_readlane_b32 s0, v254, 3
	v_readlane_b32 s1, v254, 4
	s_and_b64 s[0:1], s[0:1], exec
	s_cselect_b32 s9, s5, s3
	s_lshl_b32 s0, s4, 10
	s_and_b32 s0, s0, 0x1800
	s_and_b32 s1, s4, 1
	s_or_b32 s71, s0, s1
	s_lshl_b32 s0, s4, 9
	s_and_b32 s72, s0, 0xe00
	s_addk_i32 s72, 0xfc00
	s_add_u32 s86, s34, 0x10200000
	s_mulk_i32 s2, 0x4100
	s_addc_u32 s87, s35, 0
	s_add_i32 s73, s2, 0
	s_add_u32 s74, s34, 0x3d00000
	s_addc_u32 s75, s35, 0
	s_add_u32 s28, s34, 0x3d80000
	s_addc_u32 s77, s35, 0
	s_add_u32 s90, s34, 0x4200000
	s_addc_u32 s91, s35, 0
	s_add_u32 s94, s34, 0x4a00000
	s_addc_u32 s95, s35, 0
	s_add_u32 s78, s34, 0x3a00000
	s_addc_u32 s79, s35, 0
	s_add_u32 s29, s34, 0x5200000
	s_addc_u32 s37, s35, 0
	s_add_u32 s59, s34, 0x5a00000
	v_and_b32_e32 v252, 63, v0
	s_addc_u32 s80, s35, 0
	s_mov_b32 s96, 0
	s_branch .LBB0_651
